# RESID epilogue: batch the 16 serialized x loads per tile up front, counted vmcnt(15) waits
# speedup vs baseline: 1.0097x; 1.0097x over previous
; DI float fexp2(float x) { return __builtin_amdgcn_exp2f(x); }
; template <int EPI>
; DI void gemm_epilogue(const Ep& e, int m0, int n0) {
;     ...
; #pragma unroll
;     for (int p = 0; p < 8; ++p) {
;       const int row = p * 32 + (t >> 4), c8 = (t & 15) * 8;
;       const float4 a = *(const float4*)(T + row * 132 + c8), b = *(const float4*)(T + row * 132 + c8 + 4);
;       bf16_t* bp = e.xb + (size_t)(m0 + row) * DM + n0 + c8;
;       const uint4 xo4 = *(const uint4*)bp;
;     ...
;   if (t < 256) {
;     float rs = 1.f;
;     if (e.ss) {
;       const float* sp = e.ss + (size_t)(m0 + t) * e.nss;
;       float s = 0.f;
;       for (int i = 0; i < e.nss; ++i) s += sp[i];
;       rs = rsqrtf(s * e.inv_n + EPS);
;     }
;     ((float*)(smem + SMEM_RSTD))[t] = rs;
;   }
;   if constexpr (EPI == EPI_GU) {
;     __syncthreads();
;     const float* rstdL = (const float*)(smem + SMEM_RSTD);
; #pragma unroll
;     for (int ai = 0; ai < 2; ++ai)
; #pragma unroll
;       for (int m = 0; m < 4; ++m) {
;         const int rowb = ai * 128 + wr * 64 + m * 16 + fq * 4;
;         const f32x4 rs4 = *(const f32x4*)(rstdL + rowb);
; #pragma unroll
;         for (int bj = 0; bj < 2; ++bj) {
;           bf16_t* op = e.out + (size_t)(m0 + rowb) * e.ldo + ((n0 + bj * 128 + wc * 32) >> 1) + fr;
; #pragma unroll
;           for (int j = 0; j < 4; ++j) {
;             const float g = acc[ai][bj][m][0][j] * rs4[j], u = acc[ai][bj][m][1][j] * rs4[j];
;             const float rv = g * __builtin_amdgcn_rcpf(1.f + fexp2(-g * LOG2E)) * u;
;             op[(size_t)j * e.ldo] = (bf16_t)(pack2(rv, 0.f) & 0xffffu);
;           }
;         }
;       }
;     __syncthreads();
;     return;
;   }
;   float* T = (float*)smem;
; #pragma unroll
;   for (int bj = 0; bj < 2; ++bj) {
; #pragma unroll
;     for (int ai = 0; ai < 2; ++ai)
; #pragma unroll
;       for (int m = 0; m < 4; ++m)
; #pragma unroll
;         for (int n = 0; n < 2; ++n)
; #pragma unroll
;           for (int j = 0; j < 4; ++j)
;             T[(ai * 128 + wr * 64 + m * 16 + fq * 4 + j) * 132 + wc * 32 + n * 16 + fr] = acc[ai][bj][m][n][j];
;     __syncthreads();
.LBB0_911:
	s_or_b64 exec, exec, s[2:3]
	s_movk_i32 s2, 0x100
	v_cmp_gt_i32_e32 vcc, s2, v3
	s_waitcnt vmcnt(0)
	s_barrier
	s_and_saveexec_b64 s[2:3], vcc
	v_lshl_add_u32 v0, v3, 2, v234
	v_mov_b32_e32 v1, 1.0
	ds_write_b32 v0, v1
	s_or_b64 exec, exec, s[2:3]
	v_lshl_or_b32 v0, v148, 2, v149
	v_lshlrev_b32_e32 v1, 2, v147
	s_movk_i32 s12, 0x210
	v_lshl_or_b32 v1, v146, 7, v1
	v_mul_lo_u32 v0, v0, s12
	v_add_u32_e32 v132, v1, v0
	ds_write2_b32 v132, v104, v116 offset1:16
	ds_write2_b32 v132, v105, v117 offset0:132 offset1:148
	v_add_u32_e32 v104, 0x400, v132
	v_add_u32_e32 v105, 0x2000, v132
	ds_write2_b32 v104, v106, v118 offset0:8 offset1:24
	ds_write2_b32 v104, v107, v119 offset0:140 offset1:156
	ds_write2_b32 v105, v100, v108 offset0:64 offset1:80
	ds_write2_b32 v105, v101, v109 offset0:196 offset1:212
	v_add_u32_e32 v100, 0x2400, v132
	v_add_u32_e32 v101, 0x4000, v132
	ds_write2_b32 v100, v102, v110 offset0:72 offset1:88
	ds_write2_b32 v100, v103, v111 offset0:204 offset1:220
	ds_write2_b32 v101, v92, v96 offset0:128 offset1:144
	v_add_u32_e32 v92, 0x4400, v132
	ds_write2_b32 v92, v93, v97 offset0:4 offset1:20
	ds_write2_b32 v92, v94, v98 offset0:136 offset1:152
	v_add_u32_e32 v94, 0x6000, v132
	v_add_u32_e32 v93, 0x4800, v132
	ds_write2_b32 v94, v84, v88 offset0:192 offset1:208
	v_add_u32_e32 v84, 0x6400, v132
	v_or_b32_e32 v3, 64, v1
	ds_write2_b32 v93, v95, v99 offset0:12 offset1:28
	ds_write2_b32 v84, v85, v89 offset0:68 offset1:84
	ds_write2_b32 v84, v86, v90 offset0:200 offset1:216
	v_add_u32_e32 v85, 0x6800, v132
	v_add_u32_e32 v90, 0x10800, v0
	ds_write2_b32 v85, v87, v91 offset0:76 offset1:92
	v_add_u32_e32 v86, v1, v90
	v_add_u32_e32 v91, 0x10a10, v0
	v_add_u32_e32 v90, v3, v90
	v_add_u32_e32 v95, 0x10c20, v0
	ds_write_b32 v90, v124
	v_add_u32_e32 v90, v3, v91
	v_add_u32_e32 v96, 0x10e30, v0
	ds_write_b32 v90, v125
	v_add_u32_e32 v90, v3, v95
	ds_write_b32 v90, v126
	v_add_u32_e32 v90, v3, v96
	v_add_u32_e32 v97, 0x12900, v0
	ds_write_b32 v90, v127
	v_add_u32_e32 v90, v1, v97
	v_add_u32_e32 v98, 0x12b10, v0
	v_add_u32_e32 v97, v3, v97
	v_add_u32_e32 v99, 0x12d20, v0
	ds_write_b32 v97, v112
	v_add_u32_e32 v97, v3, v98
	v_add_u32_e32 v102, 0x12f30, v0
	ds_write_b32 v97, v113
	v_add_u32_e32 v97, v3, v99
	v_add_u32_e32 v87, v1, v91
	v_add_u32_e32 v91, v1, v98
	ds_write_b32 v97, v114
	v_add_u32_e32 v97, v3, v102
	v_add_u32_e32 v98, 0x14a00, v0
	v_add_u32_e32 v88, v1, v95
	v_add_u32_e32 v95, v1, v99
	ds_write_b32 v97, v115
	v_add_u32_e32 v97, v1, v98
	v_add_u32_e32 v99, 0x14c10, v0
	v_add_u32_e32 v89, v1, v96
	v_add_u32_e32 v96, v1, v102
	ds_write_b32 v97, v80
	v_add_u32_e32 v80, v1, v99
	v_add_u32_e32 v102, 0x14e20, v0
	ds_write_b32 v80, v81
	v_add_u32_e32 v81, v1, v102
	v_add_u32_e32 v103, 0x15030, v0
	ds_write_b32 v81, v82
	v_add_u32_e32 v82, v1, v103
	ds_write_b32 v82, v83
	v_add_u32_e32 v83, v3, v98
	ds_write_b32 v83, v76
	v_add_u32_e32 v76, v3, v99
	ds_write_b32 v76, v77
	v_add_u32_e32 v76, v3, v102
	ds_write_b32 v76, v78
	v_add_u32_e32 v76, v3, v103
	v_add_u32_e32 v83, 0x16b00, v0
	ds_write_b32 v76, v79
	v_add_u32_e32 v76, v1, v83
	ds_write_b32 v76, v72
	v_add_u32_e32 v72, 0x16d10, v0
	v_add_u32_e32 v77, v1, v72
	ds_write_b32 v77, v73
	v_add_u32_e32 v73, 0x16f20, v0
	v_add_u32_e32 v0, 0x17130, v0
	v_add_u32_e32 v78, v1, v73
	v_add_u32_e32 v79, v1, v0
	v_add_u32_e32 v1, v3, v83
	ds_write_b32 v1, v68
	v_add_u32_e32 v1, v3, v72
	ds_write_b32 v1, v69
	v_add_u32_e32 v1, v3, v73
	v_add_u32_e32 v0, v3, v0
	v_mov_b32_e32 v73, v224
	ds_write_b32 v86, v128
	ds_write_b32 v87, v129
	ds_write_b32 v88, v130
	ds_write_b32 v89, v131
	ds_write_b32 v90, v120
	ds_write_b32 v91, v121
	ds_write_b32 v95, v122
	ds_write_b32 v96, v123
	ds_write_b32 v78, v74
	ds_write_b32 v79, v75
	ds_write_b32 v1, v70
	ds_write_b32 v0, v71
	s_waitcnt lgkmcnt(0)
	s_barrier
	v_mov_b32_e32 v71, v2
	v_ashrrev_i32_e32 v72, 4, v73
	v_add_u32_e32 v68, s25, v72
	v_lshlrev_b32_e32 v0, 3, v73
	v_ashrrev_i32_e32 v69, 31, v68
	v_and_b32_e32 v99, 0x78, v0
	v_lshlrev_b64 v[0:1], 11, v[68:69]
	v_lshl_add_u64 v[0:1], s[6:7], 0, v[0:1]
	v_lshl_add_u64 v[0:1], s[8:9], 1, v[0:1]
	v_lshlrev_b32_e32 v70, 1, v99
	v_lshl_add_u64 v[102:103], v[0:1], 0, v[70:71]
	v_mov_b32_e32 v226, 0x10000
	v_mov_b32_e32 v227, 0
	global_load_dwordx4 v[156:159], v[102:103], off
	v_lshl_add_u64 v[236:237], v[102:103], 0, v[226:227]
	global_load_dwordx4 v[160:163], v[236:237], off
	v_lshl_add_u64 v[238:239], v[236:237], 0, v[226:227]
	global_load_dwordx4 v[164:167], v[238:239], off
	v_lshl_add_u64 v[240:241], v[238:239], 0, v[226:227]
	global_load_dwordx4 v[168:171], v[240:241], off
	v_lshl_add_u64 v[242:243], v[240:241], 0, v[226:227]
	global_load_dwordx4 v[172:175], v[242:243], off
	v_lshl_add_u64 v[244:245], v[242:243], 0, v[226:227]
	global_load_dwordx4 v[176:179], v[244:245], off
	v_lshl_add_u64 v[246:247], v[244:245], 0, v[226:227]
	global_load_dwordx4 v[180:183], v[246:247], off
	v_lshl_add_u64 v[248:249], v[246:247], 0, v[226:227]
	global_load_dwordx4 v[184:187], v[248:249], off
	global_load_dwordx4 v[188:191], v[102:103], off offset:256
	global_load_dwordx4 v[192:195], v[236:237], off offset:256
	global_load_dwordx4 v[196:199], v[238:239], off offset:256
	global_load_dwordx4 v[200:203], v[240:241], off offset:256
	global_load_dwordx4 v[204:207], v[242:243], off offset:256
	global_load_dwordx4 v[208:211], v[244:245], off offset:256
	global_load_dwordx4 v[212:215], v[246:247], off offset:256
	global_load_dwordx4 v[216:219], v[248:249], off offset:256
	v_and_b32_e32 v1, 64, v225
	v_lshlrev_b32_e32 v83, 2, v99
	v_xor_b32_e32 v0, 1, v225
	v_add_u32_e32 v98, 64, v1
	v_mul_lo_u32 v72, v72, s12
	v_cmp_lt_i32_e32 vcc, v0, v98
	v_add_u32_e32 v114, v83, v72
	ds_read_b128 v[110:113], v114
	v_cndmask_b32_e32 v0, v225, v0, vcc
	v_lshlrev_b32_e32 v3, 2, v0
	ds_read_b128 v[114:117], v114 offset:16
	v_xor_b32_e32 v118, 2, v225
	v_cmp_lt_i32_e32 vcc, v118, v98
	v_and_b32_e32 v73, 7, v73
	s_add_u32 s2, s0, 0xf640000
	s_addc_u32 s3, s1, 0
	s_waitcnt vmcnt(15)
; DI float h_lo(unsigned u) { return (float)__builtin_bit_cast(h2_t, u)[0]; }
; DI float h_hi(unsigned u) { return (float)__builtin_bit_cast(h2_t, u)[1]; }
; template <int EPI>
; DI void gemm_epilogue(const Ep& e, int m0, int n0) {
;     ...
; #pragma unroll
;     for (int p = 0; p < 8; ++p) {
;       const int row = p * 32 + (t >> 4), c8 = (t & 15) * 8;
;       const float4 a = *(const float4*)(T + row * 132 + c8), b = *(const float4*)(T + row * 132 + c8 + 4);
;       bf16_t* bp = e.xb + (size_t)(m0 + row) * DM + n0 + c8;
;       const uint4 xo4 = *(const uint4*)bp;
;       uint4 u;
;       u.x = pack2h(h_lo(xo4.x) + a.x, h_hi(xo4.x) + a.y); u.y = pack2h(h_lo(xo4.y) + a.z, h_hi(xo4.y) + a.w);
;       u.z = pack2h(h_lo(xo4.z) + b.x, h_hi(xo4.z) + b.y); u.w = pack2h(h_lo(xo4.w) + b.z, h_hi(xo4.w) + b.w);
;       *(uint4*)bp = u;
;       const float r0 = h_lo(u.x), r1 = h_hi(u.x), r2 = h_lo(u.y), r3 = h_hi(u.y);
;       const float r4 = h_lo(u.z), r5 = h_hi(u.z), r6 = h_lo(u.w), r7 = h_hi(u.w);
;       float s2 = r0 * r0 + r1 * r1 + r2 * r2 + r3 * r3 + r4 * r4 + r5 * r5 + r6 * r6 + r7 * r7;
;       s2 += __shfl_xor(s2, 1); s2 += __shfl_xor(s2, 2); s2 += __shfl_xor(s2, 4);
;       if ((t & 7) == 0) e.ss_out[(size_t)(m0 + row) * 16 + ((n0 + c8) >> 6)] = s2;
	v_mov_b32_e32 v106, v156
	v_mov_b32_e32 v107, v157
	v_mov_b32_e32 v108, v158
	v_mov_b32_e32 v109, v159
	v_cvt_f32_f16_e32 v0, v106
	v_cvt_f32_f16_sdwa v1, v106 dst_sel:DWORD dst_unused:UNUSED_PAD src0_sel:WORD_1
	v_cvt_f32_f16_e32 v74, v107
	v_cvt_f32_f16_sdwa v75, v107 dst_sel:DWORD dst_unused:UNUSED_PAD src0_sel:WORD_1
	s_waitcnt lgkmcnt(1)
	v_pk_add_f32 v[0:1], v[110:111], v[0:1]
	s_nop 0
	v_cvt_pk_f16_f32 v106, v0, v1
	v_pk_add_f32 v[0:1], v[112:113], v[74:75]
	v_cvt_f32_f16_sdwa v110, v106 dst_sel:DWORD dst_unused:UNUSED_PAD src0_sel:WORD_1
	v_cvt_pk_f16_f32 v107, v0, v1
	v_cvt_f32_f16_e32 v0, v109
	v_cvt_f32_f16_sdwa v1, v109 dst_sel:DWORD dst_unused:UNUSED_PAD src0_sel:WORD_1
	v_cvt_f32_f16_e32 v74, v108
	v_cvt_f32_f16_sdwa v75, v108 dst_sel:DWORD dst_unused:UNUSED_PAD src0_sel:WORD_1
	s_waitcnt lgkmcnt(0)
	v_pk_add_f32 v[0:1], v[116:117], v[0:1]
	s_nop 0
	v_cvt_pk_f16_f32 v109, v0, v1
	v_mul_f32_e32 v0, v110, v110
	v_fma_mix_f32 v0, v106, v106, v0 op_sel_hi:[1,1,0]
	v_pk_add_f32 v[74:75], v[114:115], v[74:75]
	v_fma_mix_f32 v0, v107, v107, v0 op_sel_hi:[1,1,0]
	v_cvt_pk_f16_f32 v108, v74, v75
	v_fma_mix_f32 v0, v107, v107, v0 op_sel:[1,1,0] op_sel_hi:[1,1,0]
	v_cndmask_b32_e32 v74, v225, v118, vcc
	v_fma_mix_f32 v0, v108, v108, v0 op_sel_hi:[1,1,0]
	v_lshlrev_b32_e32 v74, 2, v74
	v_fma_mix_f32 v0, v108, v108, v0 op_sel:[1,1,0] op_sel_hi:[1,1,0]
	v_xor_b32_e32 v75, 4, v225
	v_fma_mix_f32 v0, v109, v109, v0 op_sel_hi:[1,1,0]
	v_cmp_lt_i32_e32 vcc, v75, v98
	v_fma_mix_f32 v0, v109, v109, v0 op_sel:[1,1,0] op_sel_hi:[1,1,0]
	ds_bpermute_b32 v1, v3, v0
	v_cndmask_b32_e32 v75, v225, v75, vcc
	v_lshlrev_b32_e32 v75, 2, v75
	v_cmp_eq_u32_e32 vcc, 0, v73
	global_store_dwordx4 v[102:103], v[106:109], off
	s_waitcnt lgkmcnt(0)
	v_add_f32_e32 v0, v0, v1
	ds_bpermute_b32 v1, v74, v0
	s_waitcnt lgkmcnt(0)
	v_add_f32_e32 v73, v0, v1
	ds_bpermute_b32 v98, v75, v73
	v_or_b32_e32 v0, s8, v99
	v_ashrrev_i32_e32 v0, 6, v0
	v_ashrrev_i32_e32 v1, 31, v0
	s_and_saveexec_b64 s[0:1], vcc
	s_cbranch_execz .LBB0_915
	v_lshlrev_b64 v[102:103], 6, v[68:69]
	v_lshl_add_u64 v[102:103], s[2:3], 0, v[102:103]
	v_lshl_add_u64 v[102:103], v[0:1], 2, v[102:103]
	s_waitcnt lgkmcnt(0)
	v_add_f32_e32 v69, v73, v98
	global_store_dword v[102:103], v69, off
.LBB0_915:
	s_or_b64 exec, exec, s[0:1]
	v_add_u32_e32 v69, 0x4200, v72
	v_add_u32_e32 v72, 32, v68
	v_ashrrev_i32_e32 v73, 31, v72
	s_waitcnt lgkmcnt(0)
	v_lshlrev_b64 v[98:99], 11, v[72:73]
	v_lshl_add_u64 v[98:99], s[6:7], 0, v[98:99]
	v_lshl_add_u64 v[98:99], s[8:9], 1, v[98:99]
	v_lshl_add_u64 v[98:99], v[98:99], 0, v[70:71]
	v_add_u32_e32 v102, v83, v69
	ds_read_b128 v[110:113], v102
	ds_read_b128 v[114:117], v102 offset:16
	s_waitcnt vmcnt(15)
	v_mov_b32_e32 v106, v160
	v_mov_b32_e32 v107, v161
	v_mov_b32_e32 v108, v162
	v_mov_b32_e32 v109, v163
	v_cvt_f32_f16_e32 v102, v106
	v_cvt_f32_f16_sdwa v103, v106 dst_sel:DWORD dst_unused:UNUSED_PAD src0_sel:WORD_1
	s_waitcnt lgkmcnt(1)
	v_pk_add_f32 v[102:103], v[110:111], v[102:103]
	s_nop 0
	v_cvt_pk_f16_f32 v106, v102, v103
	v_cvt_f32_f16_e32 v102, v107
	v_cvt_f32_f16_sdwa v103, v107 dst_sel:DWORD dst_unused:UNUSED_PAD src0_sel:WORD_1
	v_cvt_f32_f16_sdwa v71, v106 dst_sel:DWORD dst_unused:UNUSED_PAD src0_sel:WORD_1
	v_pk_add_f32 v[102:103], v[112:113], v[102:103]
	s_nop 0
	v_cvt_pk_f16_f32 v107, v102, v103
	v_cvt_f32_f16_e32 v102, v108
	v_cvt_f32_f16_sdwa v103, v108 dst_sel:DWORD dst_unused:UNUSED_PAD src0_sel:WORD_1
	v_mul_f32_e32 v71, v71, v71
	v_fma_mix_f32 v71, v106, v106, v71 op_sel_hi:[1,1,0]
	s_waitcnt lgkmcnt(0)
	v_pk_add_f32 v[102:103], v[114:115], v[102:103]
	s_nop 0
	v_cvt_pk_f16_f32 v108, v102, v103
	v_cvt_f32_f16_e32 v102, v109
	v_cvt_f32_f16_sdwa v103, v109 dst_sel:DWORD dst_unused:UNUSED_PAD src0_sel:WORD_1
	v_fma_mix_f32 v71, v107, v107, v71 op_sel_hi:[1,1,0]
	v_pk_add_f32 v[102:103], v[116:117], v[102:103]
	v_fma_mix_f32 v71, v107, v107, v71 op_sel:[1,1,0] op_sel_hi:[1,1,0]
	v_cvt_pk_f16_f32 v109, v102, v103
	v_fma_mix_f32 v71, v108, v108, v71 op_sel_hi:[1,1,0]
	global_store_dwordx4 v[98:99], v[106:109], off
	v_fma_mix_f32 v71, v108, v108, v71 op_sel:[1,1,0] op_sel_hi:[1,1,0]
	s_nop 0
	v_fma_mix_f32 v71, v109, v109, v71 op_sel_hi:[1,1,0]
	s_nop 0
	v_fma_mix_f32 v71, v109, v109, v71 op_sel:[1,1,0] op_sel_hi:[1,1,0]
	ds_bpermute_b32 v98, v3, v71
	s_waitcnt lgkmcnt(0)
	v_add_f32_e32 v71, v71, v98
	ds_bpermute_b32 v98, v74, v71
	s_waitcnt lgkmcnt(0)
	v_add_f32_e32 v71, v71, v98
	ds_bpermute_b32 v98, v75, v71
	s_and_saveexec_b64 s[0:1], vcc
	s_cbranch_execz .LBB0_917
	v_lshlrev_b64 v[72:73], 6, v[72:73]
	v_lshl_add_u64 v[72:73], s[2:3], 0, v[72:73]
	v_lshl_add_u64 v[72:73], v[0:1], 2, v[72:73]
	s_waitcnt lgkmcnt(0)
	v_add_f32_e32 v71, v71, v98
	global_store_dword v[72:73], v71, off
; DI float h_lo(unsigned u) { return (float)__builtin_bit_cast(h2_t, u)[0]; }
; DI float h_hi(unsigned u) { return (float)__builtin_bit_cast(h2_t, u)[1]; }
; template <int EPI>
; DI void gemm_epilogue(const Ep& e, int m0, int n0) {
;     ...
; #pragma unroll
;     for (int p = 0; p < 8; ++p) {
;       const int row = p * 32 + (t >> 4), c8 = (t & 15) * 8;
;       const float4 a = *(const float4*)(T + row * 132 + c8), b = *(const float4*)(T + row * 132 + c8 + 4);
;       bf16_t* bp = e.xb + (size_t)(m0 + row) * DM + n0 + c8;
;       const uint4 xo4 = *(const uint4*)bp;
;       uint4 u;
;       u.x = pack2h(h_lo(xo4.x) + a.x, h_hi(xo4.x) + a.y); u.y = pack2h(h_lo(xo4.y) + a.z, h_hi(xo4.y) + a.w);
;       u.z = pack2h(h_lo(xo4.z) + b.x, h_hi(xo4.z) + b.y); u.w = pack2h(h_lo(xo4.w) + b.z, h_hi(xo4.w) + b.w);
;       *(uint4*)bp = u;
;       const float r0 = h_lo(u.x), r1 = h_hi(u.x), r2 = h_lo(u.y), r3 = h_hi(u.y);
;       const float r4 = h_lo(u.z), r5 = h_hi(u.z), r6 = h_lo(u.w), r7 = h_hi(u.w);
;       float s2 = r0 * r0 + r1 * r1 + r2 * r2 + r3 * r3 + r4 * r4 + r5 * r5 + r6 * r6 + r7 * r7;
;       s2 += __shfl_xor(s2, 1); s2 += __shfl_xor(s2, 2); s2 += __shfl_xor(s2, 4);
;       if ((t & 7) == 0) e.ss_out[(size_t)(m0 + row) * 16 + ((n0 + c8) >> 6)] = s2;
.LBB0_917:
	s_or_b64 exec, exec, s[0:1]
	v_add_u32_e32 v72, 64, v68
	v_ashrrev_i32_e32 v73, 31, v72
	s_waitcnt lgkmcnt(0)
	v_lshlrev_b64 v[98:99], 11, v[72:73]
	v_lshl_add_u64 v[98:99], s[6:7], 0, v[98:99]
	v_lshl_add_u64 v[98:99], s[8:9], 1, v[98:99]
	v_mov_b32_e32 v71, v2
	v_lshl_add_u64 v[98:99], v[98:99], 0, v[70:71]
	v_add_u32_e32 v69, 0x4200, v69
	v_add_u32_e32 v102, v83, v69
	ds_read_b128 v[110:113], v102
	ds_read_b128 v[114:117], v102 offset:16
	s_waitcnt vmcnt(15)
	v_mov_b32_e32 v106, v164
	v_mov_b32_e32 v107, v165
	v_mov_b32_e32 v108, v166
	v_mov_b32_e32 v109, v167
	v_cvt_f32_f16_e32 v102, v106
	v_cvt_f32_f16_sdwa v103, v106 dst_sel:DWORD dst_unused:UNUSED_PAD src0_sel:WORD_1
	s_waitcnt lgkmcnt(1)
	v_pk_add_f32 v[102:103], v[110:111], v[102:103]
	s_nop 0
	v_cvt_pk_f16_f32 v106, v102, v103
	v_cvt_f32_f16_e32 v102, v107
	v_cvt_f32_f16_sdwa v103, v107 dst_sel:DWORD dst_unused:UNUSED_PAD src0_sel:WORD_1
	v_pk_add_f32 v[102:103], v[112:113], v[102:103]
	s_nop 0
	v_cvt_pk_f16_f32 v107, v102, v103
	v_cvt_f32_f16_e32 v102, v108
	v_cvt_f32_f16_sdwa v103, v108 dst_sel:DWORD dst_unused:UNUSED_PAD src0_sel:WORD_1
	s_waitcnt lgkmcnt(0)
	v_pk_add_f32 v[102:103], v[114:115], v[102:103]
	s_nop 0
	v_cvt_pk_f16_f32 v108, v102, v103
	v_cvt_f32_f16_e32 v102, v109
	v_cvt_f32_f16_sdwa v103, v109 dst_sel:DWORD dst_unused:UNUSED_PAD src0_sel:WORD_1
	v_pk_add_f32 v[102:103], v[116:117], v[102:103]
	s_nop 0
	v_cvt_pk_f16_f32 v109, v102, v103
	global_store_dwordx4 v[98:99], v[106:109], off
	v_cvt_f32_f16_sdwa v98, v106 dst_sel:DWORD dst_unused:UNUSED_PAD src0_sel:WORD_1
	v_mul_f32_e32 v98, v98, v98
	v_fma_mix_f32 v98, v106, v106, v98 op_sel_hi:[1,1,0]
	s_nop 0
	v_fma_mix_f32 v98, v107, v107, v98 op_sel_hi:[1,1,0]
	s_nop 0
	v_fma_mix_f32 v98, v107, v107, v98 op_sel:[1,1,0] op_sel_hi:[1,1,0]
	s_nop 0
	v_fma_mix_f32 v98, v108, v108, v98 op_sel_hi:[1,1,0]
	s_nop 0
	v_fma_mix_f32 v98, v108, v108, v98 op_sel:[1,1,0] op_sel_hi:[1,1,0]
	s_nop 0
	v_fma_mix_f32 v98, v109, v109, v98 op_sel_hi:[1,1,0]
	s_nop 0
	v_fma_mix_f32 v98, v109, v109, v98 op_sel:[1,1,0] op_sel_hi:[1,1,0]
	ds_bpermute_b32 v99, v3, v98
	s_waitcnt lgkmcnt(0)
	v_add_f32_e32 v98, v98, v99
	ds_bpermute_b32 v99, v74, v98
	s_waitcnt lgkmcnt(0)
	v_add_f32_e32 v98, v98, v99
	ds_bpermute_b32 v99, v75, v98
	s_and_saveexec_b64 s[0:1], vcc
	s_cbranch_execz .LBB0_919
	v_lshlrev_b64 v[72:73], 6, v[72:73]
	v_lshl_add_u64 v[72:73], s[2:3], 0, v[72:73]
	v_lshl_add_u64 v[72:73], v[0:1], 2, v[72:73]
	s_waitcnt lgkmcnt(0)
	v_add_f32_e32 v98, v98, v99
	global_store_dword v[72:73], v98, off
.LBB0_919:
	s_or_b64 exec, exec, s[0:1]
	v_add_u32_e32 v72, 0x60, v68
	v_ashrrev_i32_e32 v73, 31, v72
	s_waitcnt lgkmcnt(0)
	v_lshlrev_b64 v[98:99], 11, v[72:73]
	v_lshl_add_u64 v[98:99], s[6:7], 0, v[98:99]
	v_lshl_add_u64 v[98:99], s[8:9], 1, v[98:99]
	v_lshl_add_u64 v[98:99], v[98:99], 0, v[70:71]
	v_add_u32_e32 v69, 0x4200, v69
	v_add_u32_e32 v102, v83, v69
	ds_read_b128 v[110:113], v102
	ds_read_b128 v[114:117], v102 offset:16
	s_waitcnt vmcnt(15)
	v_mov_b32_e32 v106, v168
	v_mov_b32_e32 v107, v169
	v_mov_b32_e32 v108, v170
	v_mov_b32_e32 v109, v171
	v_cvt_f32_f16_e32 v102, v106
	v_cvt_f32_f16_sdwa v103, v106 dst_sel:DWORD dst_unused:UNUSED_PAD src0_sel:WORD_1
	s_waitcnt lgkmcnt(1)
	v_pk_add_f32 v[102:103], v[110:111], v[102:103]
	s_nop 0
	v_cvt_pk_f16_f32 v106, v102, v103
	v_cvt_f32_f16_e32 v102, v107
	v_cvt_f32_f16_sdwa v103, v107 dst_sel:DWORD dst_unused:UNUSED_PAD src0_sel:WORD_1
	v_cvt_f32_f16_sdwa v71, v106 dst_sel:DWORD dst_unused:UNUSED_PAD src0_sel:WORD_1
	v_pk_add_f32 v[102:103], v[112:113], v[102:103]
	s_nop 0
	v_cvt_pk_f16_f32 v107, v102, v103
	v_cvt_f32_f16_e32 v102, v108
	v_cvt_f32_f16_sdwa v103, v108 dst_sel:DWORD dst_unused:UNUSED_PAD src0_sel:WORD_1
	v_mul_f32_e32 v71, v71, v71
	v_fma_mix_f32 v71, v106, v106, v71 op_sel_hi:[1,1,0]
	s_waitcnt lgkmcnt(0)
	v_pk_add_f32 v[102:103], v[114:115], v[102:103]
	s_nop 0
	v_cvt_pk_f16_f32 v108, v102, v103
	v_cvt_f32_f16_e32 v102, v109
	v_cvt_f32_f16_sdwa v103, v109 dst_sel:DWORD dst_unused:UNUSED_PAD src0_sel:WORD_1
	v_fma_mix_f32 v71, v107, v107, v71 op_sel_hi:[1,1,0]
	v_pk_add_f32 v[102:103], v[116:117], v[102:103]
	v_fma_mix_f32 v71, v107, v107, v71 op_sel:[1,1,0] op_sel_hi:[1,1,0]
	v_cvt_pk_f16_f32 v109, v102, v103
	v_fma_mix_f32 v71, v108, v108, v71 op_sel_hi:[1,1,0]
	global_store_dwordx4 v[98:99], v[106:109], off
	v_fma_mix_f32 v71, v108, v108, v71 op_sel:[1,1,0] op_sel_hi:[1,1,0]
	s_nop 0
	v_fma_mix_f32 v71, v109, v109, v71 op_sel_hi:[1,1,0]
	s_nop 0
	v_fma_mix_f32 v71, v109, v109, v71 op_sel:[1,1,0] op_sel_hi:[1,1,0]
	ds_bpermute_b32 v98, v3, v71
	s_waitcnt lgkmcnt(0)
	v_add_f32_e32 v71, v71, v98
	ds_bpermute_b32 v98, v74, v71
	s_waitcnt lgkmcnt(0)
	v_add_f32_e32 v71, v71, v98
	ds_bpermute_b32 v98, v75, v71
	s_and_saveexec_b64 s[0:1], vcc
	s_cbranch_execz .LBB0_921
	v_lshlrev_b64 v[72:73], 6, v[72:73]
	v_lshl_add_u64 v[72:73], s[2:3], 0, v[72:73]
	v_lshl_add_u64 v[72:73], v[0:1], 2, v[72:73]
	s_waitcnt lgkmcnt(0)
	v_add_f32_e32 v71, v71, v98
	global_store_dword v[72:73], v71, off
; DI float h_lo(unsigned u) { return (float)__builtin_bit_cast(h2_t, u)[0]; }
; DI float h_hi(unsigned u) { return (float)__builtin_bit_cast(h2_t, u)[1]; }
; template <int EPI>
; DI void gemm_epilogue(const Ep& e, int m0, int n0) {
;     ...
; #pragma unroll
;     for (int p = 0; p < 8; ++p) {
;       const int row = p * 32 + (t >> 4), c8 = (t & 15) * 8;
;       const float4 a = *(const float4*)(T + row * 132 + c8), b = *(const float4*)(T + row * 132 + c8 + 4);
;       bf16_t* bp = e.xb + (size_t)(m0 + row) * DM + n0 + c8;
;       const uint4 xo4 = *(const uint4*)bp;
;       uint4 u;
;       u.x = pack2h(h_lo(xo4.x) + a.x, h_hi(xo4.x) + a.y); u.y = pack2h(h_lo(xo4.y) + a.z, h_hi(xo4.y) + a.w);
;       u.z = pack2h(h_lo(xo4.z) + b.x, h_hi(xo4.z) + b.y); u.w = pack2h(h_lo(xo4.w) + b.z, h_hi(xo4.w) + b.w);
;       *(uint4*)bp = u;
;       const float r0 = h_lo(u.x), r1 = h_hi(u.x), r2 = h_lo(u.y), r3 = h_hi(u.y);
;       const float r4 = h_lo(u.z), r5 = h_hi(u.z), r6 = h_lo(u.w), r7 = h_hi(u.w);
;       float s2 = r0 * r0 + r1 * r1 + r2 * r2 + r3 * r3 + r4 * r4 + r5 * r5 + r6 * r6 + r7 * r7;
;       s2 += __shfl_xor(s2, 1); s2 += __shfl_xor(s2, 2); s2 += __shfl_xor(s2, 4);
;       if ((t & 7) == 0) e.ss_out[(size_t)(m0 + row) * 16 + ((n0 + c8) >> 6)] = s2;
.LBB0_921:
	s_or_b64 exec, exec, s[0:1]
	v_add_u32_e32 v72, 0x80, v68
	v_ashrrev_i32_e32 v73, 31, v72
	s_waitcnt lgkmcnt(0)
	v_lshlrev_b64 v[98:99], 11, v[72:73]
	v_lshl_add_u64 v[98:99], s[6:7], 0, v[98:99]
	v_lshl_add_u64 v[98:99], s[8:9], 1, v[98:99]
	v_mov_b32_e32 v71, v2
	v_lshl_add_u64 v[98:99], v[98:99], 0, v[70:71]
	v_add_u32_e32 v69, 0x4200, v69
	v_add_u32_e32 v83, v83, v69
	ds_read_b128 v[110:113], v83
	ds_read_b128 v[114:117], v83 offset:16
	s_waitcnt vmcnt(15)
	v_mov_b32_e32 v106, v172
	v_mov_b32_e32 v107, v173
	v_mov_b32_e32 v108, v174
	v_mov_b32_e32 v109, v175
	v_cvt_f32_f16_e32 v102, v106
	v_cvt_f32_f16_sdwa v103, v106 dst_sel:DWORD dst_unused:UNUSED_PAD src0_sel:WORD_1
	s_waitcnt lgkmcnt(1)
	v_pk_add_f32 v[102:103], v[110:111], v[102:103]
	s_nop 0
	v_cvt_pk_f16_f32 v106, v102, v103
	v_cvt_f32_f16_e32 v102, v107
	v_cvt_f32_f16_sdwa v103, v107 dst_sel:DWORD dst_unused:UNUSED_PAD src0_sel:WORD_1
	v_cvt_f32_f16_sdwa v69, v106 dst_sel:DWORD dst_unused:UNUSED_PAD src0_sel:WORD_1
	v_pk_add_f32 v[102:103], v[112:113], v[102:103]
	s_nop 0
	v_cvt_pk_f16_f32 v107, v102, v103
	v_cvt_f32_f16_e32 v102, v108
	v_cvt_f32_f16_sdwa v103, v108 dst_sel:DWORD dst_unused:UNUSED_PAD src0_sel:WORD_1
	v_mul_f32_e32 v69, v69, v69
	v_fma_mix_f32 v69, v106, v106, v69 op_sel_hi:[1,1,0]
	s_waitcnt lgkmcnt(0)
	v_pk_add_f32 v[102:103], v[114:115], v[102:103]
	s_nop 0
	v_cvt_pk_f16_f32 v108, v102, v103
	v_cvt_f32_f16_e32 v102, v109
	v_cvt_f32_f16_sdwa v103, v109 dst_sel:DWORD dst_unused:UNUSED_PAD src0_sel:WORD_1
	v_fma_mix_f32 v69, v107, v107, v69 op_sel_hi:[1,1,0]
	v_pk_add_f32 v[102:103], v[116:117], v[102:103]
	v_fma_mix_f32 v69, v107, v107, v69 op_sel:[1,1,0] op_sel_hi:[1,1,0]
	v_cvt_pk_f16_f32 v109, v102, v103
	v_fma_mix_f32 v69, v108, v108, v69 op_sel_hi:[1,1,0]
	global_store_dwordx4 v[98:99], v[106:109], off
	v_fma_mix_f32 v69, v108, v108, v69 op_sel:[1,1,0] op_sel_hi:[1,1,0]
	s_nop 0
	v_fma_mix_f32 v69, v109, v109, v69 op_sel_hi:[1,1,0]
	s_nop 0
	v_fma_mix_f32 v69, v109, v109, v69 op_sel:[1,1,0] op_sel_hi:[1,1,0]
	ds_bpermute_b32 v98, v3, v69
	s_waitcnt lgkmcnt(0)
	v_add_f32_e32 v69, v69, v98
	ds_bpermute_b32 v98, v74, v69
	s_waitcnt lgkmcnt(0)
	v_add_f32_e32 v69, v69, v98
	ds_bpermute_b32 v98, v75, v69
	s_and_saveexec_b64 s[0:1], vcc
	s_cbranch_execz .LBB0_923
	v_lshlrev_b64 v[72:73], 6, v[72:73]
	v_lshl_add_u64 v[72:73], s[2:3], 0, v[72:73]
	v_lshl_add_u64 v[72:73], v[0:1], 2, v[72:73]
	s_waitcnt lgkmcnt(0)
	v_add_f32_e32 v69, v69, v98
	global_store_dword v[72:73], v69, off
.LBB0_923:
	s_or_b64 exec, exec, s[0:1]
	v_add_u32_e32 v72, 0xa0, v68
	v_ashrrev_i32_e32 v73, 31, v72
	s_waitcnt lgkmcnt(0)
	v_lshlrev_b64 v[98:99], 11, v[72:73]
	v_lshl_add_u64 v[98:99], s[6:7], 0, v[98:99]
	v_lshl_add_u64 v[98:99], s[8:9], 1, v[98:99]
	v_lshl_add_u64 v[98:99], v[98:99], 0, v[70:71]
	ds_read_b128 v[110:113], v83 offset:16896
	ds_read_b128 v[114:117], v83 offset:16912
	s_waitcnt vmcnt(15)
	v_mov_b32_e32 v106, v176
	v_mov_b32_e32 v107, v177
	v_mov_b32_e32 v108, v178
	v_mov_b32_e32 v109, v179
	v_cvt_f32_f16_e32 v102, v106
	v_cvt_f32_f16_sdwa v103, v106 dst_sel:DWORD dst_unused:UNUSED_PAD src0_sel:WORD_1
	s_waitcnt lgkmcnt(1)
	v_pk_add_f32 v[102:103], v[110:111], v[102:103]
	s_nop 0
	v_cvt_pk_f16_f32 v106, v102, v103
	v_cvt_f32_f16_e32 v102, v107
	v_cvt_f32_f16_sdwa v103, v107 dst_sel:DWORD dst_unused:UNUSED_PAD src0_sel:WORD_1
	v_cvt_f32_f16_sdwa v69, v106 dst_sel:DWORD dst_unused:UNUSED_PAD src0_sel:WORD_1
	v_pk_add_f32 v[102:103], v[112:113], v[102:103]
	s_nop 0
	v_cvt_pk_f16_f32 v107, v102, v103
	v_cvt_f32_f16_e32 v102, v108
	v_cvt_f32_f16_sdwa v103, v108 dst_sel:DWORD dst_unused:UNUSED_PAD src0_sel:WORD_1
	v_mul_f32_e32 v69, v69, v69
	v_fma_mix_f32 v69, v106, v106, v69 op_sel_hi:[1,1,0]
	s_waitcnt lgkmcnt(0)
	v_pk_add_f32 v[102:103], v[114:115], v[102:103]
	s_nop 0
	v_cvt_pk_f16_f32 v108, v102, v103
	v_cvt_f32_f16_e32 v102, v109
	v_cvt_f32_f16_sdwa v103, v109 dst_sel:DWORD dst_unused:UNUSED_PAD src0_sel:WORD_1
	v_fma_mix_f32 v69, v107, v107, v69 op_sel_hi:[1,1,0]
	v_pk_add_f32 v[102:103], v[116:117], v[102:103]
	v_fma_mix_f32 v69, v107, v107, v69 op_sel:[1,1,0] op_sel_hi:[1,1,0]
	v_cvt_pk_f16_f32 v109, v102, v103
	v_fma_mix_f32 v69, v108, v108, v69 op_sel_hi:[1,1,0]
	global_store_dwordx4 v[98:99], v[106:109], off
	v_fma_mix_f32 v69, v108, v108, v69 op_sel:[1,1,0] op_sel_hi:[1,1,0]
	s_nop 0
	v_fma_mix_f32 v69, v109, v109, v69 op_sel_hi:[1,1,0]
	s_nop 0
	v_fma_mix_f32 v69, v109, v109, v69 op_sel:[1,1,0] op_sel_hi:[1,1,0]
	ds_bpermute_b32 v71, v3, v69
	s_waitcnt lgkmcnt(0)
	v_add_f32_e32 v69, v69, v71
	ds_bpermute_b32 v71, v74, v69
	s_waitcnt lgkmcnt(0)
	v_add_f32_e32 v69, v69, v71
	ds_bpermute_b32 v71, v75, v69
	s_and_saveexec_b64 s[0:1], vcc
	s_cbranch_execz .LBB0_925
	v_lshlrev_b64 v[72:73], 6, v[72:73]
	v_lshl_add_u64 v[72:73], s[2:3], 0, v[72:73]
	v_lshl_add_u64 v[72:73], v[0:1], 2, v[72:73]
	s_waitcnt lgkmcnt(0)
	v_add_f32_e32 v69, v69, v71
	global_store_dword v[72:73], v69, off
; DI float h_lo(unsigned u) { return (float)__builtin_bit_cast(h2_t, u)[0]; }
; DI float h_hi(unsigned u) { return (float)__builtin_bit_cast(h2_t, u)[1]; }
; template <int EPI>
; DI void gemm_epilogue(const Ep& e, int m0, int n0) {
;     ...
; #pragma unroll
;     for (int p = 0; p < 8; ++p) {
;       const int row = p * 32 + (t >> 4), c8 = (t & 15) * 8;
;       const float4 a = *(const float4*)(T + row * 132 + c8), b = *(const float4*)(T + row * 132 + c8 + 4);
;       bf16_t* bp = e.xb + (size_t)(m0 + row) * DM + n0 + c8;
;       const uint4 xo4 = *(const uint4*)bp;
;       uint4 u;
;       u.x = pack2h(h_lo(xo4.x) + a.x, h_hi(xo4.x) + a.y); u.y = pack2h(h_lo(xo4.y) + a.z, h_hi(xo4.y) + a.w);
;       u.z = pack2h(h_lo(xo4.z) + b.x, h_hi(xo4.z) + b.y); u.w = pack2h(h_lo(xo4.w) + b.z, h_hi(xo4.w) + b.w);
;       *(uint4*)bp = u;
;       const float r0 = h_lo(u.x), r1 = h_hi(u.x), r2 = h_lo(u.y), r3 = h_hi(u.y);
;       const float r4 = h_lo(u.z), r5 = h_hi(u.z), r6 = h_lo(u.w), r7 = h_hi(u.w);
;       float s2 = r0 * r0 + r1 * r1 + r2 * r2 + r3 * r3 + r4 * r4 + r5 * r5 + r6 * r6 + r7 * r7;
;       s2 += __shfl_xor(s2, 1); s2 += __shfl_xor(s2, 2); s2 += __shfl_xor(s2, 4);
;       if ((t & 7) == 0) e.ss_out[(size_t)(m0 + row) * 16 + ((n0 + c8) >> 6)] = s2;
.LBB0_925:
	s_or_b64 exec, exec, s[0:1]
	v_add_u32_e32 v72, 0xc0, v68
	v_ashrrev_i32_e32 v73, 31, v72
	v_lshlrev_b64 v[98:99], 11, v[72:73]
	v_lshl_add_u64 v[98:99], s[6:7], 0, v[98:99]
	v_lshl_add_u64 v[98:99], s[8:9], 1, v[98:99]
	s_waitcnt lgkmcnt(0)
	v_mov_b32_e32 v71, v2
	v_lshl_add_u64 v[98:99], v[98:99], 0, v[70:71]
	ds_read_b128 v[110:113], v83 offset:33792
	ds_read_b128 v[114:117], v83 offset:33808
	s_waitcnt vmcnt(15)
	v_mov_b32_e32 v106, v180
	v_mov_b32_e32 v107, v181
	v_mov_b32_e32 v108, v182
	v_mov_b32_e32 v109, v183
	v_cvt_f32_f16_e32 v102, v106
	v_cvt_f32_f16_sdwa v103, v106 dst_sel:DWORD dst_unused:UNUSED_PAD src0_sel:WORD_1
	s_waitcnt lgkmcnt(1)
	v_pk_add_f32 v[102:103], v[110:111], v[102:103]
	s_nop 0
	v_cvt_pk_f16_f32 v106, v102, v103
	v_cvt_f32_f16_e32 v102, v107
	v_cvt_f32_f16_sdwa v103, v107 dst_sel:DWORD dst_unused:UNUSED_PAD src0_sel:WORD_1
	v_cvt_f32_f16_sdwa v69, v106 dst_sel:DWORD dst_unused:UNUSED_PAD src0_sel:WORD_1
	v_pk_add_f32 v[102:103], v[112:113], v[102:103]
	s_nop 0
	v_cvt_pk_f16_f32 v107, v102, v103
	v_cvt_f32_f16_e32 v102, v108
	v_cvt_f32_f16_sdwa v103, v108 dst_sel:DWORD dst_unused:UNUSED_PAD src0_sel:WORD_1
	v_mul_f32_e32 v69, v69, v69
	v_fma_mix_f32 v69, v106, v106, v69 op_sel_hi:[1,1,0]
	s_waitcnt lgkmcnt(0)
	v_pk_add_f32 v[102:103], v[114:115], v[102:103]
	s_nop 0
	v_cvt_pk_f16_f32 v108, v102, v103
	v_cvt_f32_f16_e32 v102, v109
	v_cvt_f32_f16_sdwa v103, v109 dst_sel:DWORD dst_unused:UNUSED_PAD src0_sel:WORD_1
	v_fma_mix_f32 v69, v107, v107, v69 op_sel_hi:[1,1,0]
	v_pk_add_f32 v[102:103], v[116:117], v[102:103]
	v_fma_mix_f32 v69, v107, v107, v69 op_sel:[1,1,0] op_sel_hi:[1,1,0]
	v_cvt_pk_f16_f32 v109, v102, v103
	v_fma_mix_f32 v69, v108, v108, v69 op_sel_hi:[1,1,0]
	global_store_dwordx4 v[98:99], v[106:109], off
	v_fma_mix_f32 v69, v108, v108, v69 op_sel:[1,1,0] op_sel_hi:[1,1,0]
	s_nop 0
	v_fma_mix_f32 v69, v109, v109, v69 op_sel_hi:[1,1,0]
	s_nop 0
	v_fma_mix_f32 v69, v109, v109, v69 op_sel:[1,1,0] op_sel_hi:[1,1,0]
	ds_bpermute_b32 v98, v3, v69
	s_waitcnt lgkmcnt(0)
	v_add_f32_e32 v69, v69, v98
	ds_bpermute_b32 v98, v74, v69
	s_waitcnt lgkmcnt(0)
	v_add_f32_e32 v69, v69, v98
	ds_bpermute_b32 v98, v75, v69
	s_and_saveexec_b64 s[0:1], vcc
	s_cbranch_execz .LBB0_927
	v_lshlrev_b64 v[72:73], 6, v[72:73]
	v_lshl_add_u64 v[72:73], s[2:3], 0, v[72:73]
	v_lshl_add_u64 v[72:73], v[0:1], 2, v[72:73]
	s_waitcnt lgkmcnt(0)
	v_add_f32_e32 v69, v69, v98
	global_store_dword v[72:73], v69, off
.LBB0_927:
	s_or_b64 exec, exec, s[0:1]
	v_add_u32_e32 v68, 0xe0, v68
	v_ashrrev_i32_e32 v69, 31, v68
	v_lshlrev_b64 v[72:73], 11, v[68:69]
	v_lshl_add_u64 v[72:73], s[6:7], 0, v[72:73]
	v_lshl_add_u64 v[72:73], s[8:9], 1, v[72:73]
	s_waitcnt lgkmcnt(0)
	v_lshl_add_u64 v[98:99], v[72:73], 0, v[70:71]
	ds_read_b128 v[106:109], v83 offset:50688
	ds_read_b128 v[110:113], v83 offset:50704
	s_waitcnt vmcnt(15)
	v_mov_b32_e32 v70, v184
	v_mov_b32_e32 v71, v185
	v_mov_b32_e32 v72, v186
	v_mov_b32_e32 v73, v187
	v_cvt_f32_f16_e32 v102, v70
	v_cvt_f32_f16_sdwa v103, v70 dst_sel:DWORD dst_unused:UNUSED_PAD src0_sel:WORD_1
	s_waitcnt lgkmcnt(1)
	v_pk_add_f32 v[102:103], v[106:107], v[102:103]
	s_nop 0
	v_cvt_pk_f16_f32 v70, v102, v103
	v_cvt_f32_f16_e32 v102, v71
	v_cvt_f32_f16_sdwa v103, v71 dst_sel:DWORD dst_unused:UNUSED_PAD src0_sel:WORD_1
	v_cvt_f32_f16_sdwa v83, v70 dst_sel:DWORD dst_unused:UNUSED_PAD src0_sel:WORD_1
	v_pk_add_f32 v[102:103], v[108:109], v[102:103]
	s_nop 0
	v_cvt_pk_f16_f32 v71, v102, v103
	v_cvt_f32_f16_e32 v102, v72
	v_cvt_f32_f16_sdwa v103, v72 dst_sel:DWORD dst_unused:UNUSED_PAD src0_sel:WORD_1
	v_mul_f32_e32 v83, v83, v83
	s_waitcnt lgkmcnt(0)
	v_pk_add_f32 v[102:103], v[110:111], v[102:103]
	s_nop 0
	v_cvt_pk_f16_f32 v72, v102, v103
	v_cvt_f32_f16_e32 v102, v73
	v_cvt_f32_f16_sdwa v103, v73 dst_sel:DWORD dst_unused:UNUSED_PAD src0_sel:WORD_1
	v_pk_add_f32 v[102:103], v[112:113], v[102:103]
	s_nop 0
	v_cvt_pk_f16_f32 v73, v102, v103
	global_store_dwordx4 v[98:99], v[70:73], off
	s_nop 1
	v_fma_mix_f32 v70, v70, v70, v83 op_sel_hi:[1,1,0]
	s_nop 0
	v_fma_mix_f32 v70, v71, v71, v70 op_sel_hi:[1,1,0]
	s_nop 0
	v_fma_mix_f32 v70, v71, v71, v70 op_sel:[1,1,0] op_sel_hi:[1,1,0]
	s_nop 0
	v_fma_mix_f32 v70, v72, v72, v70 op_sel_hi:[1,1,0]
	s_nop 0
	v_fma_mix_f32 v70, v72, v72, v70 op_sel:[1,1,0] op_sel_hi:[1,1,0]
	s_nop 0
	v_fma_mix_f32 v70, v73, v73, v70 op_sel_hi:[1,1,0]
	s_nop 0
	v_fma_mix_f32 v70, v73, v73, v70 op_sel:[1,1,0] op_sel_hi:[1,1,0]
	ds_bpermute_b32 v71, v3, v70
	s_waitcnt lgkmcnt(0)
	v_add_f32_e32 v70, v70, v71
	ds_bpermute_b32 v71, v74, v70
	s_waitcnt lgkmcnt(0)
	v_add_f32_e32 v70, v70, v71
	ds_bpermute_b32 v71, v75, v70
	s_and_saveexec_b64 s[0:1], vcc
	s_cbranch_execz .LBB0_929
	v_lshlrev_b64 v[68:69], 6, v[68:69]
	v_lshl_add_u64 v[68:69], s[2:3], 0, v[68:69]
	v_lshl_add_u64 v[0:1], v[0:1], 2, v[68:69]
	s_waitcnt lgkmcnt(0)
	v_add_f32_e32 v68, v70, v71
	global_store_dword v[0:1], v68, off
; DI float h_lo(unsigned u) { return (float)__builtin_bit_cast(h2_t, u)[0]; }
; DI float h_hi(unsigned u) { return (float)__builtin_bit_cast(h2_t, u)[1]; }
; template <int EPI>
; DI void gemm_epilogue(const Ep& e, int m0, int n0) {
;     ...
; #pragma unroll
;     for (int p = 0; p < 8; ++p) {
;       const int row = p * 32 + (t >> 4), c8 = (t & 15) * 8;
;       const float4 a = *(const float4*)(T + row * 132 + c8), b = *(const float4*)(T + row * 132 + c8 + 4);
;       bf16_t* bp = e.xb + (size_t)(m0 + row) * DM + n0 + c8;
;       const uint4 xo4 = *(const uint4*)bp;
;       uint4 u;
;       u.x = pack2h(h_lo(xo4.x) + a.x, h_hi(xo4.x) + a.y); u.y = pack2h(h_lo(xo4.y) + a.z, h_hi(xo4.y) + a.w);
;       u.z = pack2h(h_lo(xo4.z) + b.x, h_hi(xo4.z) + b.y); u.w = pack2h(h_lo(xo4.w) + b.z, h_hi(xo4.w) + b.w);
;       *(uint4*)bp = u;
;       const float r0 = h_lo(u.x), r1 = h_hi(u.x), r2 = h_lo(u.y), r3 = h_hi(u.y);
;       const float r4 = h_lo(u.z), r5 = h_hi(u.z), r6 = h_lo(u.w), r7 = h_hi(u.w);
;       float s2 = r0 * r0 + r1 * r1 + r2 * r2 + r3 * r3 + r4 * r4 + r5 * r5 + r6 * r6 + r7 * r7;
;       s2 += __shfl_xor(s2, 1); s2 += __shfl_xor(s2, 2); s2 += __shfl_xor(s2, 4);
;       if ((t & 7) == 0) e.ss_out[(size_t)(m0 + row) * 16 + ((n0 + c8) >> 6)] = s2;
;     ...
; #pragma unroll
;   for (int bj = 0; bj < 2; ++bj) {
; #pragma unroll
;     for (int ai = 0; ai < 2; ++ai)
; #pragma unroll
;       for (int m = 0; m < 4; ++m)
; #pragma unroll
;         for (int n = 0; n < 2; ++n)
; #pragma unroll
;           for (int j = 0; j < 4; ++j)
;             T[(ai * 128 + wr * 64 + m * 16 + fq * 4 + j) * 132 + wc * 32 + n * 16 + fr] = acc[ai][bj][m][n][j];
;     __syncthreads();
.LBB0_929:
	s_or_b64 exec, exec, s[0:1]
	s_waitcnt lgkmcnt(0)
	s_barrier
	ds_write2_b32 v132, v4, v20 offset1:16
	ds_write2_b32 v132, v5, v21 offset0:132 offset1:148
	ds_write2_b32 v104, v6, v22 offset0:8 offset1:24
	ds_write2_b32 v104, v7, v23 offset0:140 offset1:156
	ds_write2_b32 v105, v8, v24 offset0:64 offset1:80
	ds_write2_b32 v105, v9, v25 offset0:196 offset1:212
	ds_write2_b32 v100, v10, v26 offset0:72 offset1:88
	ds_write2_b32 v100, v11, v27 offset0:204 offset1:220
	ds_write2_b32 v101, v12, v28 offset0:128 offset1:144
	ds_write2_b32 v92, v13, v29 offset0:4 offset1:20
	ds_write2_b32 v92, v14, v30 offset0:136 offset1:152
	ds_write2_b32 v93, v15, v31 offset0:12 offset1:28
	ds_write2_b32 v94, v16, v32 offset0:192 offset1:208
	ds_write2_b32 v84, v17, v33 offset0:68 offset1:84
	ds_write2_b32 v84, v18, v34 offset0:200 offset1:216
	ds_write2_b32 v85, v19, v35 offset0:76 offset1:92
	ds_write2_b32 v86, v36, v52 offset1:16
	ds_write2_b32 v87, v37, v53 offset1:16
	ds_write2_b32 v88, v38, v54 offset1:16
	ds_write2_b32 v89, v39, v55 offset1:16
	ds_write2_b32 v90, v40, v56 offset1:16
	ds_write2_b32 v91, v41, v57 offset1:16
	ds_write2_b32 v95, v42, v58 offset1:16
	ds_write2_b32 v96, v43, v59 offset1:16
	ds_write2_b32 v97, v44, v60 offset1:16
	ds_write2_b32 v80, v45, v61 offset1:16
	ds_write2_b32 v81, v46, v62 offset1:16
	ds_write2_b32 v82, v47, v63 offset1:16
	ds_write2_b32 v76, v48, v64 offset1:16
	ds_write2_b32 v77, v49, v65 offset1:16
	ds_write2_b32 v78, v50, v66 offset1:16
	ds_write2_b32 v79, v51, v67 offset1:16
	v_mov_b32_e32 v9, v224
	s_waitcnt lgkmcnt(0)
	s_barrier
	v_mov_b32_e32 v7, v2
	v_ashrrev_i32_e32 v8, 4, v9
	v_add_u32_e32 v4, s25, v8
	v_lshlrev_b32_e32 v0, 3, v9
	v_ashrrev_i32_e32 v5, 31, v4
	v_and_b32_e32 v30, 0x78, v0
	v_lshlrev_b64 v[0:1], 11, v[4:5]
	v_lshl_add_u64 v[0:1], s[6:7], 0, v[0:1]
	v_lshl_add_u64 v[0:1], s[8:9], 1, v[0:1]
	v_lshlrev_b32_e32 v6, 1, v30
	v_lshl_add_u64 v[24:25], v[0:1], 0, v[6:7]
	s_movk_i32 s0, 0x210
	v_mul_lo_u32 v8, v8, s0
	v_lshlrev_b32_e32 v10, 2, v30
	v_add_u32_e32 v0, v10, v8
	ds_read_b128 v[16:19], v0
	ds_read_b128 v[20:23], v0 offset:16
	v_and_b32_e32 v9, 7, v9
	v_cmp_eq_u32_e32 vcc, 0, v9
	s_waitcnt vmcnt(15)
	v_mov_b32_e32 v12, v188
	v_mov_b32_e32 v13, v189
	v_mov_b32_e32 v14, v190
	v_mov_b32_e32 v15, v191
	v_cvt_f32_f16_e32 v0, v12
	v_cvt_f32_f16_sdwa v1, v12 dst_sel:DWORD dst_unused:UNUSED_PAD src0_sel:WORD_1
	v_cvt_f32_f16_e32 v12, v13
	v_cvt_f32_f16_sdwa v13, v13 dst_sel:DWORD dst_unused:UNUSED_PAD src0_sel:WORD_1
	v_cvt_f32_f16_e32 v26, v14
	v_cvt_f32_f16_sdwa v27, v14 dst_sel:DWORD dst_unused:UNUSED_PAD src0_sel:WORD_1
	s_waitcnt lgkmcnt(1)
	v_pk_add_f32 v[0:1], v[16:17], v[0:1]
	v_cvt_f32_f16_e32 v28, v15
	v_cvt_f32_f16_sdwa v29, v15 dst_sel:DWORD dst_unused:UNUSED_PAD src0_sel:WORD_1
	v_pk_add_f32 v[14:15], v[18:19], v[12:13]
	v_cvt_pk_f16_f32 v12, v0, v1
	v_cvt_f32_f16_sdwa v11, v12 dst_sel:DWORD dst_unused:UNUSED_PAD src0_sel:WORD_1
	s_waitcnt lgkmcnt(0)
	v_pk_add_f32 v[0:1], v[20:21], v[26:27]
	v_cvt_pk_f16_f32 v13, v14, v15
	v_cvt_pk_f16_f32 v14, v0, v1
	v_pk_add_f32 v[0:1], v[22:23], v[28:29]
	s_nop 0
	v_cvt_pk_f16_f32 v15, v0, v1
	v_mul_f32_e32 v0, v11, v11
	v_fma_mix_f32 v0, v12, v12, v0 op_sel_hi:[1,1,0]
	global_store_dwordx4 v[24:25], v[12:15], off offset:256
	v_fma_mix_f32 v0, v13, v13, v0 op_sel_hi:[1,1,0]
	s_nop 0
	v_fma_mix_f32 v0, v13, v13, v0 op_sel:[1,1,0] op_sel_hi:[1,1,0]
	s_nop 0
	v_fma_mix_f32 v0, v14, v14, v0 op_sel_hi:[1,1,0]
	s_nop 0
	v_fma_mix_f32 v0, v14, v14, v0 op_sel:[1,1,0] op_sel_hi:[1,1,0]
	s_nop 0
	v_fma_mix_f32 v0, v15, v15, v0 op_sel_hi:[1,1,0]
	s_nop 0
	v_fma_mix_f32 v0, v15, v15, v0 op_sel:[1,1,0] op_sel_hi:[1,1,0]
	ds_bpermute_b32 v1, v3, v0
	s_waitcnt lgkmcnt(0)
	v_add_f32_e32 v0, v0, v1
	ds_bpermute_b32 v1, v74, v0
	s_waitcnt lgkmcnt(0)
	v_add_f32_e32 v9, v0, v1
	ds_bpermute_b32 v11, v75, v9
	v_or_b32_e32 v0, s30, v30
	v_ashrrev_i32_e32 v0, 6, v0
	v_ashrrev_i32_e32 v1, 31, v0
	s_and_saveexec_b64 s[0:1], vcc
	s_cbranch_execz .LBB0_931
	v_lshlrev_b64 v[12:13], 6, v[4:5]
	v_lshl_add_u64 v[12:13], s[2:3], 0, v[12:13]
	v_lshl_add_u64 v[12:13], v[0:1], 2, v[12:13]
	s_waitcnt lgkmcnt(0)
	v_add_f32_e32 v5, v9, v11
	global_store_dword v[12:13], v5, off
.LBB0_931:
	s_or_b64 exec, exec, s[0:1]
	v_add_u32_e32 v5, 0x4200, v8
	v_add_u32_e32 v8, 32, v4
	v_ashrrev_i32_e32 v9, 31, v8
	v_lshlrev_b64 v[12:13], 11, v[8:9]
	v_lshl_add_u64 v[12:13], s[6:7], 0, v[12:13]
	v_lshl_add_u64 v[12:13], s[8:9], 1, v[12:13]
	v_lshl_add_u64 v[24:25], v[12:13], 0, v[6:7]
	s_waitcnt lgkmcnt(0)
	v_add_u32_e32 v11, v10, v5
	ds_read_b128 v[16:19], v11
	ds_read_b128 v[20:23], v11 offset:16
	s_waitcnt vmcnt(15)
	v_mov_b32_e32 v12, v192
	v_mov_b32_e32 v13, v193
	v_mov_b32_e32 v14, v194
	v_mov_b32_e32 v15, v195
	v_cvt_f32_f16_e32 v26, v12
	v_cvt_f32_f16_sdwa v27, v12 dst_sel:DWORD dst_unused:UNUSED_PAD src0_sel:WORD_1
	s_waitcnt lgkmcnt(1)
	v_pk_add_f32 v[16:17], v[16:17], v[26:27]
	s_nop 0
	v_cvt_pk_f16_f32 v12, v16, v17
	v_cvt_f32_f16_e32 v16, v13
	v_cvt_f32_f16_sdwa v17, v13 dst_sel:DWORD dst_unused:UNUSED_PAD src0_sel:WORD_1
	v_cvt_f32_f16_sdwa v7, v12 dst_sel:DWORD dst_unused:UNUSED_PAD src0_sel:WORD_1
	v_pk_add_f32 v[16:17], v[18:19], v[16:17]
	s_nop 0
	v_cvt_pk_f16_f32 v13, v16, v17
	v_cvt_f32_f16_e32 v16, v14
	v_cvt_f32_f16_sdwa v17, v14 dst_sel:DWORD dst_unused:UNUSED_PAD src0_sel:WORD_1
	v_mul_f32_e32 v7, v7, v7
	v_fma_mix_f32 v7, v12, v12, v7 op_sel_hi:[1,1,0]
	s_waitcnt lgkmcnt(0)
	v_pk_add_f32 v[16:17], v[20:21], v[16:17]
	s_nop 0
	v_cvt_pk_f16_f32 v14, v16, v17
	v_cvt_f32_f16_e32 v16, v15
	v_cvt_f32_f16_sdwa v17, v15 dst_sel:DWORD dst_unused:UNUSED_PAD src0_sel:WORD_1
	v_fma_mix_f32 v7, v13, v13, v7 op_sel_hi:[1,1,0]
	v_pk_add_f32 v[16:17], v[22:23], v[16:17]
	v_fma_mix_f32 v7, v13, v13, v7 op_sel:[1,1,0] op_sel_hi:[1,1,0]
	v_cvt_pk_f16_f32 v15, v16, v17
	v_fma_mix_f32 v7, v14, v14, v7 op_sel_hi:[1,1,0]
	global_store_dwordx4 v[24:25], v[12:15], off offset:256
	v_fma_mix_f32 v7, v14, v14, v7 op_sel:[1,1,0] op_sel_hi:[1,1,0]
	s_nop 0
	v_fma_mix_f32 v7, v15, v15, v7 op_sel_hi:[1,1,0]
	s_nop 0
	v_fma_mix_f32 v7, v15, v15, v7 op_sel:[1,1,0] op_sel_hi:[1,1,0]
	ds_bpermute_b32 v11, v3, v7
	s_waitcnt lgkmcnt(0)
	v_add_f32_e32 v7, v7, v11
	ds_bpermute_b32 v11, v74, v7
	s_waitcnt lgkmcnt(0)
	v_add_f32_e32 v7, v7, v11
	ds_bpermute_b32 v11, v75, v7
	s_and_saveexec_b64 s[0:1], vcc
	s_cbranch_execz .LBB0_933
	v_lshlrev_b64 v[8:9], 6, v[8:9]
	v_lshl_add_u64 v[8:9], s[2:3], 0, v[8:9]
	v_lshl_add_u64 v[8:9], v[0:1], 2, v[8:9]
	s_waitcnt lgkmcnt(0)
	v_add_f32_e32 v7, v7, v11
	global_store_dword v[8:9], v7, off
; DI float h_lo(unsigned u) { return (float)__builtin_bit_cast(h2_t, u)[0]; }
; DI float h_hi(unsigned u) { return (float)__builtin_bit_cast(h2_t, u)[1]; }
; template <int EPI>
; DI void gemm_epilogue(const Ep& e, int m0, int n0) {
;     ...
; #pragma unroll
;     for (int p = 0; p < 8; ++p) {
;       const int row = p * 32 + (t >> 4), c8 = (t & 15) * 8;
;       const float4 a = *(const float4*)(T + row * 132 + c8), b = *(const float4*)(T + row * 132 + c8 + 4);
;       bf16_t* bp = e.xb + (size_t)(m0 + row) * DM + n0 + c8;
;       const uint4 xo4 = *(const uint4*)bp;
;       uint4 u;
;       u.x = pack2h(h_lo(xo4.x) + a.x, h_hi(xo4.x) + a.y); u.y = pack2h(h_lo(xo4.y) + a.z, h_hi(xo4.y) + a.w);
;       u.z = pack2h(h_lo(xo4.z) + b.x, h_hi(xo4.z) + b.y); u.w = pack2h(h_lo(xo4.w) + b.z, h_hi(xo4.w) + b.w);
;       *(uint4*)bp = u;
;       const float r0 = h_lo(u.x), r1 = h_hi(u.x), r2 = h_lo(u.y), r3 = h_hi(u.y);
;       const float r4 = h_lo(u.z), r5 = h_hi(u.z), r6 = h_lo(u.w), r7 = h_hi(u.w);
;       float s2 = r0 * r0 + r1 * r1 + r2 * r2 + r3 * r3 + r4 * r4 + r5 * r5 + r6 * r6 + r7 * r7;
;       s2 += __shfl_xor(s2, 1); s2 += __shfl_xor(s2, 2); s2 += __shfl_xor(s2, 4);
;       if ((t & 7) == 0) e.ss_out[(size_t)(m0 + row) * 16 + ((n0 + c8) >> 6)] = s2;
.LBB0_933:
	s_or_b64 exec, exec, s[0:1]
	v_add_u32_e32 v8, 64, v4
	v_ashrrev_i32_e32 v9, 31, v8
	v_lshlrev_b64 v[12:13], 11, v[8:9]
	v_lshl_add_u64 v[12:13], s[6:7], 0, v[12:13]
	v_lshl_add_u64 v[12:13], s[8:9], 1, v[12:13]
	v_mov_b32_e32 v7, v2
	v_lshl_add_u64 v[24:25], v[12:13], 0, v[6:7]
	v_add_u32_e32 v5, 0x4200, v5
	s_waitcnt lgkmcnt(0)
	v_add_u32_e32 v11, v10, v5
	ds_read_b128 v[16:19], v11
	ds_read_b128 v[20:23], v11 offset:16
	s_waitcnt vmcnt(15)
	v_mov_b32_e32 v12, v196
	v_mov_b32_e32 v13, v197
	v_mov_b32_e32 v14, v198
	v_mov_b32_e32 v15, v199
	v_cvt_f32_f16_e32 v26, v12
	v_cvt_f32_f16_sdwa v27, v12 dst_sel:DWORD dst_unused:UNUSED_PAD src0_sel:WORD_1
	s_waitcnt lgkmcnt(1)
	v_pk_add_f32 v[16:17], v[16:17], v[26:27]
	s_nop 0
	v_cvt_pk_f16_f32 v12, v16, v17
	v_cvt_f32_f16_e32 v16, v13
	v_cvt_f32_f16_sdwa v17, v13 dst_sel:DWORD dst_unused:UNUSED_PAD src0_sel:WORD_1
	v_cvt_f32_f16_sdwa v11, v12 dst_sel:DWORD dst_unused:UNUSED_PAD src0_sel:WORD_1
	v_pk_add_f32 v[16:17], v[18:19], v[16:17]
	s_nop 0
	v_cvt_pk_f16_f32 v13, v16, v17
	v_cvt_f32_f16_e32 v16, v14
	v_cvt_f32_f16_sdwa v17, v14 dst_sel:DWORD dst_unused:UNUSED_PAD src0_sel:WORD_1
	v_mul_f32_e32 v11, v11, v11
	v_fma_mix_f32 v11, v12, v12, v11 op_sel_hi:[1,1,0]
	s_waitcnt lgkmcnt(0)
	v_pk_add_f32 v[16:17], v[20:21], v[16:17]
	s_nop 0
	v_cvt_pk_f16_f32 v14, v16, v17
	v_cvt_f32_f16_e32 v16, v15
	v_cvt_f32_f16_sdwa v17, v15 dst_sel:DWORD dst_unused:UNUSED_PAD src0_sel:WORD_1
	v_fma_mix_f32 v11, v13, v13, v11 op_sel_hi:[1,1,0]
	v_pk_add_f32 v[16:17], v[22:23], v[16:17]
	v_fma_mix_f32 v11, v13, v13, v11 op_sel:[1,1,0] op_sel_hi:[1,1,0]
	v_cvt_pk_f16_f32 v15, v16, v17
	v_fma_mix_f32 v11, v14, v14, v11 op_sel_hi:[1,1,0]
	global_store_dwordx4 v[24:25], v[12:15], off offset:256
	v_fma_mix_f32 v11, v14, v14, v11 op_sel:[1,1,0] op_sel_hi:[1,1,0]
	s_nop 0
	v_fma_mix_f32 v11, v15, v15, v11 op_sel_hi:[1,1,0]
	s_nop 0
	v_fma_mix_f32 v11, v15, v15, v11 op_sel:[1,1,0] op_sel_hi:[1,1,0]
	ds_bpermute_b32 v12, v3, v11
	s_waitcnt lgkmcnt(0)
	v_add_f32_e32 v11, v11, v12
	ds_bpermute_b32 v12, v74, v11
	s_waitcnt lgkmcnt(0)
	v_add_f32_e32 v11, v11, v12
	ds_bpermute_b32 v12, v75, v11
	s_and_saveexec_b64 s[0:1], vcc
	s_cbranch_execz .LBB0_935
	v_lshlrev_b64 v[8:9], 6, v[8:9]
	v_lshl_add_u64 v[8:9], s[2:3], 0, v[8:9]
	v_lshl_add_u64 v[8:9], v[0:1], 2, v[8:9]
	s_waitcnt lgkmcnt(0)
	v_add_f32_e32 v11, v11, v12
	global_store_dword v[8:9], v11, off
.LBB0_935:
	s_or_b64 exec, exec, s[0:1]
	v_add_u32_e32 v8, 0x60, v4
	v_ashrrev_i32_e32 v9, 31, v8
	s_waitcnt lgkmcnt(0)
	v_lshlrev_b64 v[12:13], 11, v[8:9]
	v_lshl_add_u64 v[12:13], s[6:7], 0, v[12:13]
	v_lshl_add_u64 v[12:13], s[8:9], 1, v[12:13]
	v_lshl_add_u64 v[24:25], v[12:13], 0, v[6:7]
	v_add_u32_e32 v5, 0x4200, v5
	v_add_u32_e32 v11, v10, v5
	ds_read_b128 v[16:19], v11
	ds_read_b128 v[20:23], v11 offset:16
	s_waitcnt vmcnt(15)
	v_mov_b32_e32 v12, v200
	v_mov_b32_e32 v13, v201
	v_mov_b32_e32 v14, v202
	v_mov_b32_e32 v15, v203
	v_cvt_f32_f16_e32 v26, v12
	v_cvt_f32_f16_sdwa v27, v12 dst_sel:DWORD dst_unused:UNUSED_PAD src0_sel:WORD_1
	s_waitcnt lgkmcnt(1)
	v_pk_add_f32 v[16:17], v[16:17], v[26:27]
	s_nop 0
	v_cvt_pk_f16_f32 v12, v16, v17
	v_cvt_f32_f16_e32 v16, v13
	v_cvt_f32_f16_sdwa v17, v13 dst_sel:DWORD dst_unused:UNUSED_PAD src0_sel:WORD_1
	v_cvt_f32_f16_sdwa v7, v12 dst_sel:DWORD dst_unused:UNUSED_PAD src0_sel:WORD_1
	v_pk_add_f32 v[16:17], v[18:19], v[16:17]
	s_nop 0
	v_cvt_pk_f16_f32 v13, v16, v17
	v_cvt_f32_f16_e32 v16, v14
	v_cvt_f32_f16_sdwa v17, v14 dst_sel:DWORD dst_unused:UNUSED_PAD src0_sel:WORD_1
	v_mul_f32_e32 v7, v7, v7
	v_fma_mix_f32 v7, v12, v12, v7 op_sel_hi:[1,1,0]
	s_waitcnt lgkmcnt(0)
	v_pk_add_f32 v[16:17], v[20:21], v[16:17]
	s_nop 0
	v_cvt_pk_f16_f32 v14, v16, v17
	v_cvt_f32_f16_e32 v16, v15
	v_cvt_f32_f16_sdwa v17, v15 dst_sel:DWORD dst_unused:UNUSED_PAD src0_sel:WORD_1
	v_fma_mix_f32 v7, v13, v13, v7 op_sel_hi:[1,1,0]
	v_pk_add_f32 v[16:17], v[22:23], v[16:17]
	v_fma_mix_f32 v7, v13, v13, v7 op_sel:[1,1,0] op_sel_hi:[1,1,0]
	v_cvt_pk_f16_f32 v15, v16, v17
	v_fma_mix_f32 v7, v14, v14, v7 op_sel_hi:[1,1,0]
	global_store_dwordx4 v[24:25], v[12:15], off offset:256
	v_fma_mix_f32 v7, v14, v14, v7 op_sel:[1,1,0] op_sel_hi:[1,1,0]
	s_nop 0
	v_fma_mix_f32 v7, v15, v15, v7 op_sel_hi:[1,1,0]
	s_nop 0
	v_fma_mix_f32 v7, v15, v15, v7 op_sel:[1,1,0] op_sel_hi:[1,1,0]
	ds_bpermute_b32 v11, v3, v7
	s_waitcnt lgkmcnt(0)
	v_add_f32_e32 v7, v7, v11
	ds_bpermute_b32 v11, v74, v7
	s_waitcnt lgkmcnt(0)
	v_add_f32_e32 v7, v7, v11
	ds_bpermute_b32 v11, v75, v7
	s_and_saveexec_b64 s[0:1], vcc
	s_cbranch_execz .LBB0_937
	v_lshlrev_b64 v[8:9], 6, v[8:9]
	v_lshl_add_u64 v[8:9], s[2:3], 0, v[8:9]
	v_lshl_add_u64 v[8:9], v[0:1], 2, v[8:9]
	s_waitcnt lgkmcnt(0)
	v_add_f32_e32 v7, v7, v11
	global_store_dword v[8:9], v7, off
; DI float h_lo(unsigned u) { return (float)__builtin_bit_cast(h2_t, u)[0]; }
; DI float h_hi(unsigned u) { return (float)__builtin_bit_cast(h2_t, u)[1]; }
; template <int EPI>
; DI void gemm_epilogue(const Ep& e, int m0, int n0) {
;     ...
; #pragma unroll
;     for (int p = 0; p < 8; ++p) {
;       const int row = p * 32 + (t >> 4), c8 = (t & 15) * 8;
;       const float4 a = *(const float4*)(T + row * 132 + c8), b = *(const float4*)(T + row * 132 + c8 + 4);
;       bf16_t* bp = e.xb + (size_t)(m0 + row) * DM + n0 + c8;
;       const uint4 xo4 = *(const uint4*)bp;
;       uint4 u;
;       u.x = pack2h(h_lo(xo4.x) + a.x, h_hi(xo4.x) + a.y); u.y = pack2h(h_lo(xo4.y) + a.z, h_hi(xo4.y) + a.w);
;       u.z = pack2h(h_lo(xo4.z) + b.x, h_hi(xo4.z) + b.y); u.w = pack2h(h_lo(xo4.w) + b.z, h_hi(xo4.w) + b.w);
;       *(uint4*)bp = u;
;       const float r0 = h_lo(u.x), r1 = h_hi(u.x), r2 = h_lo(u.y), r3 = h_hi(u.y);
;       const float r4 = h_lo(u.z), r5 = h_hi(u.z), r6 = h_lo(u.w), r7 = h_hi(u.w);
;       float s2 = r0 * r0 + r1 * r1 + r2 * r2 + r3 * r3 + r4 * r4 + r5 * r5 + r6 * r6 + r7 * r7;
;       s2 += __shfl_xor(s2, 1); s2 += __shfl_xor(s2, 2); s2 += __shfl_xor(s2, 4);
;       if ((t & 7) == 0) e.ss_out[(size_t)(m0 + row) * 16 + ((n0 + c8) >> 6)] = s2;
.LBB0_937:
	s_or_b64 exec, exec, s[0:1]
	v_add_u32_e32 v8, 0x80, v4
	v_ashrrev_i32_e32 v9, 31, v8
	v_lshlrev_b64 v[12:13], 11, v[8:9]
	v_lshl_add_u64 v[12:13], s[6:7], 0, v[12:13]
	v_lshl_add_u64 v[12:13], s[8:9], 1, v[12:13]
	v_mov_b32_e32 v7, v2
	v_lshl_add_u64 v[24:25], v[12:13], 0, v[6:7]
	v_add_u32_e32 v5, 0x4200, v5
	v_add_u32_e32 v10, v10, v5
	ds_read_b128 v[16:19], v10
	ds_read_b128 v[20:23], v10 offset:16
	s_waitcnt vmcnt(15)
	v_mov_b32_e32 v12, v204
	v_mov_b32_e32 v13, v205
	v_mov_b32_e32 v14, v206
	v_mov_b32_e32 v15, v207
	v_cvt_f32_f16_e32 v26, v12
	v_cvt_f32_f16_sdwa v27, v12 dst_sel:DWORD dst_unused:UNUSED_PAD src0_sel:WORD_1
	s_waitcnt lgkmcnt(1)
	v_pk_add_f32 v[16:17], v[16:17], v[26:27]
	s_nop 0
	v_cvt_pk_f16_f32 v12, v16, v17
	v_cvt_f32_f16_e32 v16, v13
	v_cvt_f32_f16_sdwa v17, v13 dst_sel:DWORD dst_unused:UNUSED_PAD src0_sel:WORD_1
	v_cvt_f32_f16_sdwa v5, v12 dst_sel:DWORD dst_unused:UNUSED_PAD src0_sel:WORD_1
	v_pk_add_f32 v[16:17], v[18:19], v[16:17]
	s_nop 0
	v_cvt_pk_f16_f32 v13, v16, v17
	v_cvt_f32_f16_e32 v16, v14
	v_cvt_f32_f16_sdwa v17, v14 dst_sel:DWORD dst_unused:UNUSED_PAD src0_sel:WORD_1
	v_mul_f32_e32 v5, v5, v5
	v_fma_mix_f32 v5, v12, v12, v5 op_sel_hi:[1,1,0]
	s_waitcnt lgkmcnt(0)
	v_pk_add_f32 v[16:17], v[20:21], v[16:17]
	s_nop 0
	v_cvt_pk_f16_f32 v14, v16, v17
	v_cvt_f32_f16_e32 v16, v15
	v_cvt_f32_f16_sdwa v17, v15 dst_sel:DWORD dst_unused:UNUSED_PAD src0_sel:WORD_1
	v_fma_mix_f32 v5, v13, v13, v5 op_sel_hi:[1,1,0]
	v_pk_add_f32 v[16:17], v[22:23], v[16:17]
	v_fma_mix_f32 v5, v13, v13, v5 op_sel:[1,1,0] op_sel_hi:[1,1,0]
	v_cvt_pk_f16_f32 v15, v16, v17
	v_fma_mix_f32 v5, v14, v14, v5 op_sel_hi:[1,1,0]
	global_store_dwordx4 v[24:25], v[12:15], off offset:256
	v_fma_mix_f32 v5, v14, v14, v5 op_sel:[1,1,0] op_sel_hi:[1,1,0]
	s_nop 0
	v_fma_mix_f32 v5, v15, v15, v5 op_sel_hi:[1,1,0]
	s_nop 0
	v_fma_mix_f32 v5, v15, v15, v5 op_sel:[1,1,0] op_sel_hi:[1,1,0]
	ds_bpermute_b32 v11, v3, v5
	s_waitcnt lgkmcnt(0)
	v_add_f32_e32 v5, v5, v11
	ds_bpermute_b32 v11, v74, v5
	s_waitcnt lgkmcnt(0)
	v_add_f32_e32 v5, v5, v11
	ds_bpermute_b32 v11, v75, v5
	s_and_saveexec_b64 s[0:1], vcc
	s_cbranch_execz .LBB0_939
	v_lshlrev_b64 v[8:9], 6, v[8:9]
	v_lshl_add_u64 v[8:9], s[2:3], 0, v[8:9]
	v_lshl_add_u64 v[8:9], v[0:1], 2, v[8:9]
	s_waitcnt lgkmcnt(0)
	v_add_f32_e32 v5, v5, v11
	global_store_dword v[8:9], v5, off
.LBB0_939:
	s_or_b64 exec, exec, s[0:1]
	v_add_u32_e32 v8, 0xa0, v4
	v_ashrrev_i32_e32 v9, 31, v8
	v_lshlrev_b64 v[12:13], 11, v[8:9]
	v_lshl_add_u64 v[12:13], s[6:7], 0, v[12:13]
	v_lshl_add_u64 v[12:13], s[8:9], 1, v[12:13]
	v_lshl_add_u64 v[24:25], v[12:13], 0, v[6:7]
	ds_read_b128 v[16:19], v10 offset:16896
	ds_read_b128 v[20:23], v10 offset:16912
	s_waitcnt vmcnt(15)
	v_mov_b32_e32 v12, v208
	v_mov_b32_e32 v13, v209
	v_mov_b32_e32 v14, v210
	v_mov_b32_e32 v15, v211
	v_cvt_f32_f16_e32 v26, v12
	v_cvt_f32_f16_sdwa v27, v12 dst_sel:DWORD dst_unused:UNUSED_PAD src0_sel:WORD_1
	s_waitcnt lgkmcnt(1)
	v_pk_add_f32 v[16:17], v[16:17], v[26:27]
	s_nop 0
	v_cvt_pk_f16_f32 v12, v16, v17
	v_cvt_f32_f16_e32 v16, v13
	v_cvt_f32_f16_sdwa v17, v13 dst_sel:DWORD dst_unused:UNUSED_PAD src0_sel:WORD_1
	v_cvt_f32_f16_sdwa v5, v12 dst_sel:DWORD dst_unused:UNUSED_PAD src0_sel:WORD_1
	v_pk_add_f32 v[16:17], v[18:19], v[16:17]
	s_nop 0
	v_cvt_pk_f16_f32 v13, v16, v17
	v_cvt_f32_f16_e32 v16, v14
	v_cvt_f32_f16_sdwa v17, v14 dst_sel:DWORD dst_unused:UNUSED_PAD src0_sel:WORD_1
	v_mul_f32_e32 v5, v5, v5
	v_fma_mix_f32 v5, v12, v12, v5 op_sel_hi:[1,1,0]
	s_waitcnt lgkmcnt(0)
	v_pk_add_f32 v[16:17], v[20:21], v[16:17]
	s_nop 0
	v_cvt_pk_f16_f32 v14, v16, v17
	v_cvt_f32_f16_e32 v16, v15
	v_cvt_f32_f16_sdwa v17, v15 dst_sel:DWORD dst_unused:UNUSED_PAD src0_sel:WORD_1
	v_fma_mix_f32 v5, v13, v13, v5 op_sel_hi:[1,1,0]
	v_pk_add_f32 v[16:17], v[22:23], v[16:17]
	v_fma_mix_f32 v5, v13, v13, v5 op_sel:[1,1,0] op_sel_hi:[1,1,0]
	v_cvt_pk_f16_f32 v15, v16, v17
	v_fma_mix_f32 v5, v14, v14, v5 op_sel_hi:[1,1,0]
	global_store_dwordx4 v[24:25], v[12:15], off offset:256
	v_fma_mix_f32 v5, v14, v14, v5 op_sel:[1,1,0] op_sel_hi:[1,1,0]
	s_nop 0
	v_fma_mix_f32 v5, v15, v15, v5 op_sel_hi:[1,1,0]
	s_nop 0
	v_fma_mix_f32 v5, v15, v15, v5 op_sel:[1,1,0] op_sel_hi:[1,1,0]
	ds_bpermute_b32 v7, v3, v5
	s_waitcnt lgkmcnt(0)
	v_add_f32_e32 v5, v5, v7
	ds_bpermute_b32 v7, v74, v5
	s_waitcnt lgkmcnt(0)
	v_add_f32_e32 v5, v5, v7
	ds_bpermute_b32 v7, v75, v5
	s_and_saveexec_b64 s[0:1], vcc
	s_cbranch_execz .LBB0_941
	v_lshlrev_b64 v[8:9], 6, v[8:9]
	v_lshl_add_u64 v[8:9], s[2:3], 0, v[8:9]
	v_lshl_add_u64 v[8:9], v[0:1], 2, v[8:9]
	s_waitcnt lgkmcnt(0)
	v_add_f32_e32 v5, v5, v7
	global_store_dword v[8:9], v5, off
; DI float h_lo(unsigned u) { return (float)__builtin_bit_cast(h2_t, u)[0]; }
; DI float h_hi(unsigned u) { return (float)__builtin_bit_cast(h2_t, u)[1]; }
; template <int EPI>
; DI void gemm_epilogue(const Ep& e, int m0, int n0) {
;     ...
; #pragma unroll
;     for (int p = 0; p < 8; ++p) {
;       const int row = p * 32 + (t >> 4), c8 = (t & 15) * 8;
;       const float4 a = *(const float4*)(T + row * 132 + c8), b = *(const float4*)(T + row * 132 + c8 + 4);
;       bf16_t* bp = e.xb + (size_t)(m0 + row) * DM + n0 + c8;
;       const uint4 xo4 = *(const uint4*)bp;
;       uint4 u;
;       u.x = pack2h(h_lo(xo4.x) + a.x, h_hi(xo4.x) + a.y); u.y = pack2h(h_lo(xo4.y) + a.z, h_hi(xo4.y) + a.w);
;       u.z = pack2h(h_lo(xo4.z) + b.x, h_hi(xo4.z) + b.y); u.w = pack2h(h_lo(xo4.w) + b.z, h_hi(xo4.w) + b.w);
;       *(uint4*)bp = u;
;       const float r0 = h_lo(u.x), r1 = h_hi(u.x), r2 = h_lo(u.y), r3 = h_hi(u.y);
;       const float r4 = h_lo(u.z), r5 = h_hi(u.z), r6 = h_lo(u.w), r7 = h_hi(u.w);
;       float s2 = r0 * r0 + r1 * r1 + r2 * r2 + r3 * r3 + r4 * r4 + r5 * r5 + r6 * r6 + r7 * r7;
;       s2 += __shfl_xor(s2, 1); s2 += __shfl_xor(s2, 2); s2 += __shfl_xor(s2, 4);
;       if ((t & 7) == 0) e.ss_out[(size_t)(m0 + row) * 16 + ((n0 + c8) >> 6)] = s2;
.LBB0_941:
	s_or_b64 exec, exec, s[0:1]
	v_add_u32_e32 v8, 0xc0, v4
	v_ashrrev_i32_e32 v9, 31, v8
	v_lshlrev_b64 v[12:13], 11, v[8:9]
	v_lshl_add_u64 v[12:13], s[6:7], 0, v[12:13]
	v_lshl_add_u64 v[12:13], s[8:9], 1, v[12:13]
	s_waitcnt lgkmcnt(0)
	v_mov_b32_e32 v7, v2
	v_lshl_add_u64 v[24:25], v[12:13], 0, v[6:7]
	ds_read_b128 v[16:19], v10 offset:33792
	ds_read_b128 v[20:23], v10 offset:33808
	s_waitcnt vmcnt(15)
	v_mov_b32_e32 v12, v212
	v_mov_b32_e32 v13, v213
	v_mov_b32_e32 v14, v214
	v_mov_b32_e32 v15, v215
	v_cvt_f32_f16_e32 v26, v12
	v_cvt_f32_f16_sdwa v27, v12 dst_sel:DWORD dst_unused:UNUSED_PAD src0_sel:WORD_1
	s_waitcnt lgkmcnt(1)
	v_pk_add_f32 v[16:17], v[16:17], v[26:27]
	s_nop 0
	v_cvt_pk_f16_f32 v12, v16, v17
	v_cvt_f32_f16_e32 v16, v13
	v_cvt_f32_f16_sdwa v17, v13 dst_sel:DWORD dst_unused:UNUSED_PAD src0_sel:WORD_1
	v_cvt_f32_f16_sdwa v5, v12 dst_sel:DWORD dst_unused:UNUSED_PAD src0_sel:WORD_1
	v_pk_add_f32 v[16:17], v[18:19], v[16:17]
	s_nop 0
	v_cvt_pk_f16_f32 v13, v16, v17
	v_cvt_f32_f16_e32 v16, v14
	v_cvt_f32_f16_sdwa v17, v14 dst_sel:DWORD dst_unused:UNUSED_PAD src0_sel:WORD_1
	v_mul_f32_e32 v5, v5, v5
	v_fma_mix_f32 v5, v12, v12, v5 op_sel_hi:[1,1,0]
	s_waitcnt lgkmcnt(0)
	v_pk_add_f32 v[16:17], v[20:21], v[16:17]
	s_nop 0
	v_cvt_pk_f16_f32 v14, v16, v17
	v_cvt_f32_f16_e32 v16, v15
	v_cvt_f32_f16_sdwa v17, v15 dst_sel:DWORD dst_unused:UNUSED_PAD src0_sel:WORD_1
	v_fma_mix_f32 v5, v13, v13, v5 op_sel_hi:[1,1,0]
	v_pk_add_f32 v[16:17], v[22:23], v[16:17]
	v_fma_mix_f32 v5, v13, v13, v5 op_sel:[1,1,0] op_sel_hi:[1,1,0]
	v_cvt_pk_f16_f32 v15, v16, v17
	v_fma_mix_f32 v5, v14, v14, v5 op_sel_hi:[1,1,0]
	global_store_dwordx4 v[24:25], v[12:15], off offset:256
	v_fma_mix_f32 v5, v14, v14, v5 op_sel:[1,1,0] op_sel_hi:[1,1,0]
	s_nop 0
	v_fma_mix_f32 v5, v15, v15, v5 op_sel_hi:[1,1,0]
	s_nop 0
	v_fma_mix_f32 v5, v15, v15, v5 op_sel:[1,1,0] op_sel_hi:[1,1,0]
	ds_bpermute_b32 v11, v3, v5
	s_waitcnt lgkmcnt(0)
	v_add_f32_e32 v5, v5, v11
	ds_bpermute_b32 v11, v74, v5
	s_waitcnt lgkmcnt(0)
	v_add_f32_e32 v5, v5, v11
	ds_bpermute_b32 v11, v75, v5
	s_and_saveexec_b64 s[0:1], vcc
	s_cbranch_execz .LBB0_943
	v_lshlrev_b64 v[8:9], 6, v[8:9]
	v_lshl_add_u64 v[8:9], s[2:3], 0, v[8:9]
	v_lshl_add_u64 v[8:9], v[0:1], 2, v[8:9]
	s_waitcnt lgkmcnt(0)
	v_add_f32_e32 v5, v5, v11
	global_store_dword v[8:9], v5, off
.LBB0_943:
	s_or_b64 exec, exec, s[0:1]
	v_add_u32_e32 v4, 0xe0, v4
	v_ashrrev_i32_e32 v5, 31, v4
	v_lshlrev_b64 v[8:9], 11, v[4:5]
	v_lshl_add_u64 v[8:9], s[6:7], 0, v[8:9]
	v_lshl_add_u64 v[8:9], s[8:9], 1, v[8:9]
	v_lshl_add_u64 v[20:21], v[8:9], 0, v[6:7]
	ds_read_b128 v[12:15], v10 offset:50688
	ds_read_b128 v[16:19], v10 offset:50704
	s_waitcnt vmcnt(15)
	v_mov_b32_e32 v6, v216
	v_mov_b32_e32 v7, v217
	v_mov_b32_e32 v8, v218
	v_mov_b32_e32 v9, v219
	v_cvt_f32_f16_e32 v10, v6
	s_waitcnt lgkmcnt(2)
	v_cvt_f32_f16_sdwa v11, v6 dst_sel:DWORD dst_unused:UNUSED_PAD src0_sel:WORD_1
	s_waitcnt lgkmcnt(1)
	v_pk_add_f32 v[10:11], v[12:13], v[10:11]
	s_nop 0
	v_cvt_pk_f16_f32 v6, v10, v11
	v_cvt_f32_f16_e32 v10, v7
	v_cvt_f32_f16_sdwa v11, v7 dst_sel:DWORD dst_unused:UNUSED_PAD src0_sel:WORD_1
	v_pk_add_f32 v[10:11], v[14:15], v[10:11]
	s_nop 0
	v_cvt_pk_f16_f32 v7, v10, v11
	v_cvt_f32_f16_e32 v10, v8
	v_cvt_f32_f16_sdwa v11, v8 dst_sel:DWORD dst_unused:UNUSED_PAD src0_sel:WORD_1
	s_waitcnt lgkmcnt(0)
	v_pk_add_f32 v[10:11], v[16:17], v[10:11]
	s_nop 0
	v_cvt_pk_f16_f32 v8, v10, v11
	v_cvt_f32_f16_e32 v10, v9
	v_cvt_f32_f16_sdwa v11, v9 dst_sel:DWORD dst_unused:UNUSED_PAD src0_sel:WORD_1
	v_pk_add_f32 v[10:11], v[18:19], v[10:11]
	s_nop 0
	v_cvt_pk_f16_f32 v9, v10, v11
	v_cvt_f32_f16_sdwa v10, v6 dst_sel:DWORD dst_unused:UNUSED_PAD src0_sel:WORD_1
	global_store_dwordx4 v[20:21], v[6:9], off offset:256
	v_mul_f32_e32 v10, v10, v10
	s_nop 0
	v_fma_mix_f32 v6, v6, v6, v10 op_sel_hi:[1,1,0]
	s_nop 0
	v_fma_mix_f32 v6, v7, v7, v6 op_sel_hi:[1,1,0]
	s_nop 0
	v_fma_mix_f32 v6, v7, v7, v6 op_sel:[1,1,0] op_sel_hi:[1,1,0]
	s_nop 0
	v_fma_mix_f32 v6, v8, v8, v6 op_sel_hi:[1,1,0]
	s_nop 0
	v_fma_mix_f32 v6, v8, v8, v6 op_sel:[1,1,0] op_sel_hi:[1,1,0]
	s_nop 0
	v_fma_mix_f32 v6, v9, v9, v6 op_sel_hi:[1,1,0]
	s_nop 0
	v_fma_mix_f32 v6, v9, v9, v6 op_sel:[1,1,0] op_sel_hi:[1,1,0]
	ds_bpermute_b32 v3, v3, v6
	s_waitcnt lgkmcnt(0)
	v_add_f32_e32 v3, v6, v3
	ds_bpermute_b32 v6, v74, v3
	s_waitcnt lgkmcnt(0)
	v_add_f32_e32 v3, v3, v6
	ds_bpermute_b32 v6, v75, v3
	s_and_saveexec_b64 s[0:1], vcc
	s_cbranch_execz .LBB0_904
	v_lshlrev_b64 v[4:5], 6, v[4:5]
	v_lshl_add_u64 v[4:5], s[2:3], 0, v[4:5]
	v_lshl_add_u64 v[0:1], v[0:1], 2, v[4:5]
	s_waitcnt lgkmcnt(0)
	v_add_f32_e32 v3, v3, v6
	global_store_dword v[0:1], v3, off
	s_branch .LBB0_904
